# grid barrier: waiters spin on the top-level arrival counter reaching its target; the separate generation bump by the last arriver (after its own atomic returned) and its ack wait are gone
# speedup vs baseline: 1.0037x; 1.0034x over previous
.LBB0_136:
	s_or_b64 exec, exec, s[8:9]
	v_cvt_f32_u32_e32 v4, v2
	s_waitcnt vmcnt(0)
	v_readfirstlane_b32 s6, v3
	v_sub_u32_e32 v3, 0, v2
	v_rcp_iflag_f32_e32 v4, v4
	v_add_u32_e32 v5, s6, v1
	v_mul_f32_e32 v4, 0x4f7ffffe, v4
	v_cvt_u32_f32_e32 v4, v4
	v_mul_lo_u32 v1, v3, v4
	v_mul_hi_u32 v1, v4, v1
	v_add_u32_e32 v1, v4, v1
	v_mul_hi_u32 v1, v5, v1
	v_mul_lo_u32 v3, v1, v2
	v_sub_u32_e32 v3, v5, v3
	v_add_u32_e32 v4, 1, v1
	v_cmp_ge_u32_e32 vcc, v3, v2
	s_nop 1
	v_cndmask_b32_e32 v1, v1, v4, vcc
	v_sub_u32_e32 v4, v3, v2
	v_cndmask_b32_e32 v3, v3, v4, vcc
	v_add_u32_e32 v4, 1, v1
	v_cmp_ge_u32_e32 vcc, v3, v2
	v_add_u32_e32 v3, 1, v5
	s_nop 0
	v_cndmask_b32_e32 v1, v1, v4, vcc
	v_mul_lo_u32 v4, v2, v1
	v_add_u32_e32 v2, v4, v2
	v_cmp_ne_u32_e32 vcc, v3, v2
	s_and_saveexec_b64 s[6:7], vcc
	s_xor_b64 s[6:7], exec, s[6:7]
	s_cbranch_execz .LBB0_151
	s_waitcnt lgkmcnt(0)
	s_add_u32 s12, s2, 0x31c3400
	s_addc_u32 s13, s3, 0
	v_add_u32_e32 v1, 1, v1
	v_mul_lo_u32 v1, v1, v0
	v_mov_b32_e32 v0, 0
	global_load_dword v0, v0, s[12:13] sc1
	s_waitcnt vmcnt(0)
	v_cmp_lt_u32_e32 vcc, v0, v1
	s_and_saveexec_b64 s[8:9], vcc
	s_cbranch_execz .LBB0_150
	s_add_u32 s10, s2, 0x31c0200
	s_addc_u32 s11, s3, 0
	s_mov_b32 s24, 1
	s_mov_b64 s[14:15], 0
	v_mov_b32_e32 v0, 0
	s_branch .LBB0_140

.LBB0_142:
	global_load_dword v2, v0, s[12:13] sc1
	s_add_i32 s24, s24, 1
	s_mov_b64 s[20:21], -1
	s_waitcnt vmcnt(0)
	v_cmp_ge_u32_e32 vcc, v2, v1
	s_orn2_b64 s[18:19], vcc, exec
	s_branch .LBB0_139

.LBB0_154:
	s_or_b64 exec, exec, s[8:9]
	v_cvt_f32_u32_e32 v3, v0
	s_waitcnt vmcnt(0)
	v_readfirstlane_b32 s6, v2
	s_add_u32 s8, s2, 0x31c3400
	s_addc_u32 s9, s3, 0
	v_rcp_iflag_f32_e32 v3, v3
	v_add_u32_e32 v1, s6, v1
	v_add_u32_e32 v4, 1, v1
	s_mov_b64 s[10:11], 0
	v_mul_f32_e32 v2, 0x4f7ffffe, v3
	v_cvt_u32_f32_e32 v2, v2
	v_sub_u32_e32 v3, 0, v0
	v_mul_lo_u32 v3, v3, v2
	v_mul_hi_u32 v3, v2, v3
	v_add_u32_e32 v2, v2, v3
	v_mul_hi_u32 v2, v1, v2
	v_mul_lo_u32 v3, v2, v0
	v_sub_u32_e32 v1, v1, v3
	v_add_u32_e32 v5, 1, v2
	v_cmp_ge_u32_e32 vcc, v1, v0
	v_sub_u32_e32 v3, v1, v0
	s_nop 0
	v_cndmask_b32_e32 v2, v2, v5, vcc
	v_cndmask_b32_e32 v1, v1, v3, vcc
	v_add_u32_e32 v3, 1, v2
	v_cmp_ge_u32_e32 vcc, v1, v0
	s_nop 1
	v_cndmask_b32_e32 v2, v2, v3, vcc
	v_mul_lo_u32 v1, v0, v2
	v_add_u32_e32 v0, v1, v0
	v_cmp_ne_u32_e32 vcc, v4, v0
	v_mov_b32_e32 v2, v0
	v_mov_b64_e32 v[0:1], s[8:9]
	s_and_saveexec_b64 s[6:7], vcc
	s_cbranch_execz .LBB0_168
	v_mov_b32_e32 v0, 0
	global_load_dword v1, v0, s[8:9] sc1
	s_mov_b64 s[14:15], 0
	s_waitcnt vmcnt(0)
	v_cmp_lt_u32_e32 vcc, v1, v2
	s_and_saveexec_b64 s[12:13], vcc
	s_cbranch_execz .LBB0_167
	s_add_u32 s10, s2, 0x31c0200
	s_addc_u32 s11, s3, 0
	s_mov_b32 s22, 1
	s_mov_b64 s[2:3], 0
	s_branch .LBB0_158

.LBB0_160:
	global_load_dword v1, v0, s[8:9] sc1
	s_add_i32 s22, s22, 1
	s_mov_b64 s[16:17], -1
	s_waitcnt vmcnt(0)
	v_cmp_ge_u32_e32 vcc, v1, v2
	s_orn2_b64 s[20:21], vcc, exec
	s_branch .LBB0_157

.LBB0_256:
	s_or_b64 exec, exec, s[10:11]
	v_cvt_f32_u32_e32 v5, v3
	s_waitcnt vmcnt(0)
	v_readfirstlane_b32 s8, v4
	v_sub_u32_e32 v4, 0, v3
	v_rcp_iflag_f32_e32 v5, v5
	v_add_u32_e32 v6, s8, v1
	v_mul_f32_e32 v5, 0x4f7ffffe, v5
	v_cvt_u32_f32_e32 v5, v5
	v_mul_lo_u32 v1, v4, v5
	v_mul_hi_u32 v1, v5, v1
	v_add_u32_e32 v1, v5, v1
	v_mul_hi_u32 v1, v6, v1
	v_mul_lo_u32 v4, v1, v3
	v_sub_u32_e32 v4, v6, v4
	v_add_u32_e32 v5, 1, v1
	v_cmp_ge_u32_e32 vcc, v4, v3
	s_nop 1
	v_cndmask_b32_e32 v1, v1, v5, vcc
	v_sub_u32_e32 v5, v4, v3
	v_cndmask_b32_e32 v4, v4, v5, vcc
	v_add_u32_e32 v5, 1, v1
	v_cmp_ge_u32_e32 vcc, v4, v3
	v_add_u32_e32 v4, 1, v6
	s_nop 0
	v_cndmask_b32_e32 v1, v1, v5, vcc
	v_mul_lo_u32 v5, v3, v1
	v_add_u32_e32 v3, v5, v3
	v_cmp_ne_u32_e32 vcc, v4, v3
	s_and_saveexec_b64 s[8:9], vcc
	s_xor_b64 s[8:9], exec, s[8:9]
	s_cbranch_execz .LBB0_270
	s_waitcnt lgkmcnt(0)
	s_add_u32 s14, s4, 0x31c3400
	s_addc_u32 s15, s5, 0
	v_add_u32_e32 v1, 1, v1
	v_mul_lo_u32 v1, v1, v2
	v_mov_b32_e32 v2, 0
	global_load_dword v2, v2, s[14:15] sc1
	s_waitcnt vmcnt(0)
	v_cmp_lt_u32_e32 vcc, v2, v1
	s_and_saveexec_b64 s[10:11], vcc
	s_cbranch_execz .LBB0_269
	s_add_u32 s12, s4, 0x31c0200
	s_addc_u32 s13, s5, 0
	s_mov_b32 s28, 1
	s_mov_b64 s[18:19], 0
	s_branch .LBB0_260

.LBB0_262:
	global_load_dword v2, v0, s[14:15] sc1
	s_add_i32 s28, s28, 1
	s_mov_b64 s[24:25], -1
	s_waitcnt vmcnt(0)
	v_cmp_ge_u32_e32 vcc, v2, v1
	s_orn2_b64 s[22:23], vcc, exec
	s_branch .LBB0_259

.LBB0_273:
	s_or_b64 exec, exec, s[10:11]
	v_cvt_f32_u32_e32 v4, v2
	s_waitcnt vmcnt(0)
	v_readfirstlane_b32 s8, v3
	s_mov_b64 s[12:13], 0
	v_rcp_iflag_f32_e32 v4, v4
	v_add_u32_e32 v1, s8, v1
	v_add_u32_e32 v5, 1, v1
	s_add_u32 s8, s4, 0x31c3400
	v_mul_f32_e32 v3, 0x4f7ffffe, v4
	v_cvt_u32_f32_e32 v3, v3
	v_sub_u32_e32 v4, 0, v2
	s_addc_u32 s9, s5, 0
	v_mul_lo_u32 v4, v4, v3
	v_mul_hi_u32 v4, v3, v4
	v_add_u32_e32 v3, v3, v4
	v_mul_hi_u32 v3, v1, v3
	v_mul_lo_u32 v4, v3, v2
	v_sub_u32_e32 v1, v1, v4
	v_add_u32_e32 v6, 1, v3
	v_cmp_ge_u32_e32 vcc, v1, v2
	v_sub_u32_e32 v4, v1, v2
	s_nop 0
	v_cndmask_b32_e32 v3, v3, v6, vcc
	v_cndmask_b32_e32 v1, v1, v4, vcc
	v_add_u32_e32 v4, 1, v3
	v_cmp_ge_u32_e32 vcc, v1, v2
	s_nop 1
	v_cndmask_b32_e32 v1, v3, v4, vcc
	v_mul_lo_u32 v3, v2, v1
	v_add_u32_e32 v2, v3, v2
	v_cmp_ne_u32_e32 vcc, v5, v2
	v_mov_b32_e32 v1, v2
	v_mov_b64_e32 v[2:3], s[8:9]
	s_and_saveexec_b64 s[10:11], vcc
	s_cbranch_execz .LBB0_285
	global_load_dword v2, v0, s[8:9] sc1
	s_mov_b64 s[18:19], 0
	s_waitcnt vmcnt(0)
	v_cmp_lt_u32_e32 vcc, v2, v1
	s_and_saveexec_b64 s[14:15], vcc
	s_cbranch_execz .LBB0_284
	s_add_u32 s12, s4, 0x31c0200
	s_addc_u32 s13, s5, 0
	s_mov_b32 s26, 1
	s_mov_b64 s[4:5], 0
	s_branch .LBB0_277

.LBB0_279:
	global_load_dword v2, v0, s[8:9] sc1
	s_add_i32 s26, s26, 1
	s_mov_b64 s[22:23], -1
	s_waitcnt vmcnt(0)
	v_cmp_ge_u32_e32 vcc, v2, v1
	s_orn2_b64 s[20:21], vcc, exec
	s_branch .LBB0_276

.LBB0_320:
	s_or_b64 exec, exec, s[12:13]
	v_cvt_f32_u32_e32 v5, v3
	s_waitcnt vmcnt(0)
	v_readfirstlane_b32 s8, v4
	v_sub_u32_e32 v4, 0, v3
	v_rcp_iflag_f32_e32 v5, v5
	v_add_u32_e32 v6, s8, v1
	v_mul_f32_e32 v5, 0x4f7ffffe, v5
	v_cvt_u32_f32_e32 v5, v5
	v_mul_lo_u32 v1, v4, v5
	v_mul_hi_u32 v1, v5, v1
	v_add_u32_e32 v1, v5, v1
	v_mul_hi_u32 v1, v6, v1
	v_mul_lo_u32 v4, v1, v3
	v_sub_u32_e32 v4, v6, v4
	v_add_u32_e32 v5, 1, v1
	v_cmp_ge_u32_e32 vcc, v4, v3
	s_nop 1
	v_cndmask_b32_e32 v1, v1, v5, vcc
	v_sub_u32_e32 v5, v4, v3
	v_cndmask_b32_e32 v4, v4, v5, vcc
	v_add_u32_e32 v5, 1, v1
	v_cmp_ge_u32_e32 vcc, v4, v3
	v_add_u32_e32 v4, 1, v6
	s_nop 0
	v_cndmask_b32_e32 v1, v1, v5, vcc
	v_mul_lo_u32 v5, v3, v1
	v_add_u32_e32 v3, v5, v3
	v_cmp_ne_u32_e32 vcc, v4, v3
	s_and_saveexec_b64 s[8:9], vcc
	s_xor_b64 s[8:9], exec, s[8:9]
	s_cbranch_execz .LBB0_334
	s_waitcnt lgkmcnt(0)
	s_add_u32 s18, s4, 0x31c3400
	s_addc_u32 s19, s5, 0
	v_add_u32_e32 v1, 1, v1
	v_mul_lo_u32 v1, v1, v2
	v_mov_b32_e32 v2, 0
	global_load_dword v2, v2, s[18:19] sc1
	s_waitcnt vmcnt(0)
	v_cmp_lt_u32_e32 vcc, v2, v1
	s_and_saveexec_b64 s[12:13], vcc
	s_cbranch_execz .LBB0_333
	s_add_u32 s14, s4, 0x31c0200
	s_addc_u32 s15, s5, 0
	s_mov_b32 s30, 1
	s_mov_b64 s[20:21], 0
	s_branch .LBB0_324

.LBB0_326:
	global_load_dword v2, v0, s[18:19] sc1
	s_add_i32 s30, s30, 1
	s_mov_b64 s[26:27], -1
	s_waitcnt vmcnt(0)
	v_cmp_ge_u32_e32 vcc, v2, v1
	s_orn2_b64 s[24:25], vcc, exec
	s_branch .LBB0_323

.LBB0_337:
	s_or_b64 exec, exec, s[12:13]
	s_waitcnt vmcnt(0)
	v_readfirstlane_b32 s8, v3
	v_sub_u32_e32 v4, 0, v2
	s_mov_b64 s[14:15], 0
	v_add_u32_e32 v3, s8, v1
	v_cvt_f32_u32_e32 v1, v2
	s_add_u32 s8, s4, 0x31c3400
	s_addc_u32 s9, s5, 0
	v_rcp_iflag_f32_e32 v1, v1
	s_nop 0
	v_mul_f32_e32 v1, 0x4f7ffffe, v1
	v_cvt_u32_f32_e32 v1, v1
	v_mul_lo_u32 v4, v4, v1
	v_mul_hi_u32 v4, v1, v4
	v_add_u32_e32 v1, v1, v4
	v_mul_hi_u32 v1, v3, v1
	v_mul_lo_u32 v4, v1, v2
	v_sub_u32_e32 v4, v3, v4
	v_cmp_ge_u32_e32 vcc, v4, v2
	v_add_u32_e32 v5, 1, v1
	v_add_u32_e32 v3, 1, v3
	v_cndmask_b32_e32 v1, v1, v5, vcc
	v_sub_u32_e32 v5, v4, v2
	v_cndmask_b32_e32 v4, v4, v5, vcc
	v_cmp_ge_u32_e32 vcc, v4, v2
	v_add_u32_e32 v4, 1, v1
	s_nop 0
	v_cndmask_b32_e32 v1, v1, v4, vcc
	v_mul_lo_u32 v4, v2, v1
	v_add_u32_e32 v2, v4, v2
	v_cmp_ne_u32_e32 vcc, v3, v2
	v_mov_b32_e32 v1, v2
	v_mov_b64_e32 v[2:3], s[8:9]
	s_and_saveexec_b64 s[12:13], vcc
	s_cbranch_execz .LBB0_349
	global_load_dword v2, v0, s[8:9] sc1
	s_mov_b64 s[20:21], 0
	s_waitcnt vmcnt(0)
	v_cmp_lt_u32_e32 vcc, v2, v1
	s_and_saveexec_b64 s[18:19], vcc
	s_cbranch_execz .LBB0_348
	s_add_u32 s14, s4, 0x31c0200
	s_addc_u32 s15, s5, 0
	s_mov_b32 s28, 1
	s_mov_b64 s[4:5], 0
	s_branch .LBB0_341

.LBB0_343:
	global_load_dword v2, v0, s[8:9] sc1
	s_add_i32 s28, s28, 1
	s_mov_b64 s[24:25], -1
	s_waitcnt vmcnt(0)
	v_cmp_ge_u32_e32 vcc, v2, v1
	s_orn2_b64 s[22:23], vcc, exec
	s_branch .LBB0_340

.LBB0_423:
	s_or_b64 exec, exec, s[12:13]
	v_cvt_f32_u32_e32 v5, v3
	s_waitcnt vmcnt(0)
	v_readfirstlane_b32 s8, v4
	v_sub_u32_e32 v4, 0, v3
	v_rcp_iflag_f32_e32 v5, v5
	v_add_u32_e32 v6, s8, v1
	v_mul_f32_e32 v5, 0x4f7ffffe, v5
	v_cvt_u32_f32_e32 v5, v5
	v_mul_lo_u32 v1, v4, v5
	v_mul_hi_u32 v1, v5, v1
	v_add_u32_e32 v1, v5, v1
	v_mul_hi_u32 v1, v6, v1
	v_mul_lo_u32 v4, v1, v3
	v_sub_u32_e32 v4, v6, v4
	v_add_u32_e32 v5, 1, v1
	v_cmp_ge_u32_e32 vcc, v4, v3
	s_nop 1
	v_cndmask_b32_e32 v1, v1, v5, vcc
	v_sub_u32_e32 v5, v4, v3
	v_cndmask_b32_e32 v4, v4, v5, vcc
	v_add_u32_e32 v5, 1, v1
	v_cmp_ge_u32_e32 vcc, v4, v3
	v_add_u32_e32 v4, 1, v6
	s_nop 0
	v_cndmask_b32_e32 v1, v1, v5, vcc
	v_mul_lo_u32 v5, v3, v1
	v_add_u32_e32 v3, v5, v3
	v_cmp_ne_u32_e32 vcc, v4, v3
	s_and_saveexec_b64 s[8:9], vcc
	s_xor_b64 s[8:9], exec, s[8:9]
	s_cbranch_execz .LBB0_437
	s_waitcnt lgkmcnt(0)
	s_add_u32 s16, s4, 0x31c3400
	s_addc_u32 s17, s5, 0
	v_add_u32_e32 v1, 1, v1
	v_mul_lo_u32 v1, v1, v2
	v_mov_b32_e32 v2, 0
	global_load_dword v2, v2, s[16:17] sc1
	s_waitcnt vmcnt(0)
	v_cmp_lt_u32_e32 vcc, v2, v1
	s_and_saveexec_b64 s[12:13], vcc
	s_cbranch_execz .LBB0_436
	s_add_u32 s14, s4, 0x31c0200
	s_addc_u32 s15, s5, 0
	s_mov_b32 s28, 1
	s_mov_b64 s[18:19], 0
	s_branch .LBB0_427

.LBB0_429:
	global_load_dword v2, v0, s[16:17] sc1
	s_add_i32 s28, s28, 1
	s_mov_b64 s[24:25], -1
	s_waitcnt vmcnt(0)
	v_cmp_ge_u32_e32 vcc, v2, v1
	s_orn2_b64 s[22:23], vcc, exec
	s_branch .LBB0_426

.LBB0_440:
	s_or_b64 exec, exec, s[12:13]
	s_waitcnt vmcnt(0)
	v_readfirstlane_b32 s8, v3
	v_sub_u32_e32 v4, 0, v2
	s_mov_b64 s[14:15], 0
	v_add_u32_e32 v3, s8, v1
	v_cvt_f32_u32_e32 v1, v2
	s_add_u32 s8, s4, 0x31c3400
	s_addc_u32 s9, s5, 0
	v_rcp_iflag_f32_e32 v1, v1
	s_nop 0
	v_mul_f32_e32 v1, 0x4f7ffffe, v1
	v_cvt_u32_f32_e32 v1, v1
	v_mul_lo_u32 v4, v4, v1
	v_mul_hi_u32 v4, v1, v4
	v_add_u32_e32 v1, v1, v4
	v_mul_hi_u32 v1, v3, v1
	v_mul_lo_u32 v4, v1, v2
	v_sub_u32_e32 v4, v3, v4
	v_cmp_ge_u32_e32 vcc, v4, v2
	v_add_u32_e32 v5, 1, v1
	v_add_u32_e32 v3, 1, v3
	v_cndmask_b32_e32 v1, v1, v5, vcc
	v_sub_u32_e32 v5, v4, v2
	v_cndmask_b32_e32 v4, v4, v5, vcc
	v_cmp_ge_u32_e32 vcc, v4, v2
	v_add_u32_e32 v4, 1, v1
	s_nop 0
	v_cndmask_b32_e32 v1, v1, v4, vcc
	v_mul_lo_u32 v4, v2, v1
	v_add_u32_e32 v2, v4, v2
	v_cmp_ne_u32_e32 vcc, v3, v2
	v_mov_b32_e32 v1, v2
	v_mov_b64_e32 v[2:3], s[8:9]
	s_and_saveexec_b64 s[12:13], vcc
	s_cbranch_execz .LBB0_452
	global_load_dword v2, v0, s[8:9] sc1
	s_mov_b64 s[18:19], 0
	s_waitcnt vmcnt(0)
	v_cmp_lt_u32_e32 vcc, v2, v1
	s_and_saveexec_b64 s[16:17], vcc
	s_cbranch_execz .LBB0_451
	s_add_u32 s14, s4, 0x31c0200
	s_addc_u32 s15, s5, 0
	s_mov_b32 s26, 1
	s_mov_b64 s[4:5], 0
	s_branch .LBB0_444

.LBB0_483:
	s_or_b64 exec, exec, s[10:11]
	v_cvt_f32_u32_e32 v5, v3
	s_waitcnt vmcnt(0)
	v_readfirstlane_b32 s8, v4
	v_sub_u32_e32 v4, 0, v3
	v_rcp_iflag_f32_e32 v5, v5
	v_add_u32_e32 v6, s8, v1
	v_mul_f32_e32 v5, 0x4f7ffffe, v5
	v_cvt_u32_f32_e32 v5, v5
	v_mul_lo_u32 v1, v4, v5
	v_mul_hi_u32 v1, v5, v1
	v_add_u32_e32 v1, v5, v1
	v_mul_hi_u32 v1, v6, v1
	v_mul_lo_u32 v4, v1, v3
	v_sub_u32_e32 v4, v6, v4
	v_add_u32_e32 v5, 1, v1
	v_cmp_ge_u32_e32 vcc, v4, v3
	s_nop 1
	v_cndmask_b32_e32 v1, v1, v5, vcc
	v_sub_u32_e32 v5, v4, v3
	v_cndmask_b32_e32 v4, v4, v5, vcc
	v_add_u32_e32 v5, 1, v1
	v_cmp_ge_u32_e32 vcc, v4, v3
	v_add_u32_e32 v4, 1, v6
	s_nop 0
	v_cndmask_b32_e32 v1, v1, v5, vcc
	v_mul_lo_u32 v5, v3, v1
	v_add_u32_e32 v3, v5, v3
	v_cmp_ne_u32_e32 vcc, v4, v3
	s_and_saveexec_b64 s[8:9], vcc
	s_xor_b64 s[8:9], exec, s[8:9]
	s_cbranch_execz .LBB0_497
	s_waitcnt lgkmcnt(0)
	s_add_u32 s14, s4, 0x31c3400
	s_addc_u32 s15, s5, 0
	v_add_u32_e32 v1, 1, v1
	v_mul_lo_u32 v1, v1, v2
	v_mov_b32_e32 v2, 0
	global_load_dword v2, v2, s[14:15] sc1
	s_waitcnt vmcnt(0)
	v_cmp_lt_u32_e32 vcc, v2, v1
	s_and_saveexec_b64 s[10:11], vcc
	s_cbranch_execz .LBB0_496
	s_add_u32 s12, s4, 0x31c0200
	s_addc_u32 s13, s5, 0
	s_mov_b32 s26, 1
	s_mov_b64 s[16:17], 0
	s_branch .LBB0_487

.LBB0_489:
	global_load_dword v2, v0, s[14:15] sc1
	s_add_i32 s26, s26, 1
	s_mov_b64 s[22:23], -1
	s_waitcnt vmcnt(0)
	v_cmp_ge_u32_e32 vcc, v2, v1
	s_orn2_b64 s[20:21], vcc, exec
	s_branch .LBB0_486

.LBB0_500:
	s_or_b64 exec, exec, s[10:11]
	s_waitcnt vmcnt(0)
	v_readfirstlane_b32 s8, v3
	v_sub_u32_e32 v4, 0, v2
	s_mov_b64 s[12:13], 0
	v_add_u32_e32 v3, s8, v1
	v_cvt_f32_u32_e32 v1, v2
	s_add_u32 s8, s4, 0x31c3400
	s_addc_u32 s9, s5, 0
	v_rcp_iflag_f32_e32 v1, v1
	s_nop 0
	v_mul_f32_e32 v1, 0x4f7ffffe, v1
	v_cvt_u32_f32_e32 v1, v1
	v_mul_lo_u32 v4, v4, v1
	v_mul_hi_u32 v4, v1, v4
	v_add_u32_e32 v1, v1, v4
	v_mul_hi_u32 v1, v3, v1
	v_mul_lo_u32 v4, v1, v2
	v_sub_u32_e32 v4, v3, v4
	v_cmp_ge_u32_e32 vcc, v4, v2
	v_add_u32_e32 v5, 1, v1
	v_add_u32_e32 v3, 1, v3
	v_cndmask_b32_e32 v1, v1, v5, vcc
	v_sub_u32_e32 v5, v4, v2
	v_cndmask_b32_e32 v4, v4, v5, vcc
	v_cmp_ge_u32_e32 vcc, v4, v2
	v_add_u32_e32 v4, 1, v1
	s_nop 0
	v_cndmask_b32_e32 v1, v1, v4, vcc
	v_mul_lo_u32 v4, v2, v1
	v_add_u32_e32 v2, v4, v2
	v_cmp_ne_u32_e32 vcc, v3, v2
	v_mov_b32_e32 v1, v2
	v_mov_b64_e32 v[2:3], s[8:9]
	s_and_saveexec_b64 s[10:11], vcc
	s_cbranch_execz .LBB0_514
	global_load_dword v2, v0, s[8:9] sc1
	s_mov_b64 s[16:17], 0
	s_waitcnt vmcnt(0)
	v_cmp_lt_u32_e32 vcc, v2, v1
	s_and_saveexec_b64 s[14:15], vcc
	s_cbranch_execz .LBB0_513
	s_add_u32 s12, s4, 0x31c0200
	s_addc_u32 s13, s5, 0
	s_mov_b32 s24, 1
	s_mov_b64 s[4:5], 0
	s_branch .LBB0_504

.LBB0_506:
	global_load_dword v2, v0, s[8:9] sc1
	s_add_i32 s24, s24, 1
	s_mov_b64 s[20:21], -1
	s_waitcnt vmcnt(0)
	v_cmp_ge_u32_e32 vcc, v2, v1
	s_orn2_b64 s[18:19], vcc, exec
	s_branch .LBB0_503

.LBB0_555:
	s_or_b64 exec, exec, s[12:13]
	v_cvt_f32_u32_e32 v5, v3
	s_waitcnt vmcnt(0)
	v_readfirstlane_b32 s10, v4
	v_sub_u32_e32 v4, 0, v3
	v_rcp_iflag_f32_e32 v5, v5
	v_add_u32_e32 v6, s10, v1
	v_mul_f32_e32 v5, 0x4f7ffffe, v5
	v_cvt_u32_f32_e32 v5, v5
	v_mul_lo_u32 v1, v4, v5
	v_mul_hi_u32 v1, v5, v1
	v_add_u32_e32 v1, v5, v1
	v_mul_hi_u32 v1, v6, v1
	v_mul_lo_u32 v4, v1, v3
	v_sub_u32_e32 v4, v6, v4
	v_add_u32_e32 v5, 1, v1
	v_cmp_ge_u32_e32 vcc, v4, v3
	s_nop 1
	v_cndmask_b32_e32 v1, v1, v5, vcc
	v_sub_u32_e32 v5, v4, v3
	v_cndmask_b32_e32 v4, v4, v5, vcc
	v_add_u32_e32 v5, 1, v1
	v_cmp_ge_u32_e32 vcc, v4, v3
	v_add_u32_e32 v4, 1, v6
	s_nop 0
	v_cndmask_b32_e32 v1, v1, v5, vcc
	v_mul_lo_u32 v5, v3, v1
	v_add_u32_e32 v3, v5, v3
	v_cmp_ne_u32_e32 vcc, v4, v3
	s_and_saveexec_b64 s[10:11], vcc
	s_xor_b64 s[10:11], exec, s[10:11]
	s_cbranch_execz .LBB0_569
	s_waitcnt lgkmcnt(0)
	s_add_u32 s16, s6, 0x31c3400
	s_addc_u32 s17, s7, 0
	v_add_u32_e32 v1, 1, v1
	v_mul_lo_u32 v1, v1, v2
	v_mov_b32_e32 v2, 0
	global_load_dword v2, v2, s[16:17] sc1
	s_waitcnt vmcnt(0)
	v_cmp_lt_u32_e32 vcc, v2, v1
	s_and_saveexec_b64 s[12:13], vcc
	s_cbranch_execz .LBB0_568
	s_add_u32 s14, s6, 0x31c0200
	s_addc_u32 s15, s7, 0
	s_mov_b32 s28, 1
	s_mov_b64 s[18:19], 0
	s_branch .LBB0_559

.LBB0_572:
	s_or_b64 exec, exec, s[12:13]
	s_waitcnt vmcnt(0)
	v_readfirstlane_b32 s10, v3
	v_sub_u32_e32 v4, 0, v2
	s_mov_b64 s[14:15], 0
	v_add_u32_e32 v3, s10, v1
	v_cvt_f32_u32_e32 v1, v2
	s_add_u32 s10, s6, 0x31c3400
	s_addc_u32 s11, s7, 0
	v_rcp_iflag_f32_e32 v1, v1
	s_nop 0
	v_mul_f32_e32 v1, 0x4f7ffffe, v1
	v_cvt_u32_f32_e32 v1, v1
	v_mul_lo_u32 v4, v4, v1
	v_mul_hi_u32 v4, v1, v4
	v_add_u32_e32 v1, v1, v4
	v_mul_hi_u32 v1, v3, v1
	v_mul_lo_u32 v4, v1, v2
	v_sub_u32_e32 v4, v3, v4
	v_cmp_ge_u32_e32 vcc, v4, v2
	v_add_u32_e32 v5, 1, v1
	v_add_u32_e32 v3, 1, v3
	v_cndmask_b32_e32 v1, v1, v5, vcc
	v_sub_u32_e32 v5, v4, v2
	v_cndmask_b32_e32 v4, v4, v5, vcc
	v_cmp_ge_u32_e32 vcc, v4, v2
	v_add_u32_e32 v4, 1, v1
	s_nop 0
	v_cndmask_b32_e32 v1, v1, v4, vcc
	v_mul_lo_u32 v4, v2, v1
	v_add_u32_e32 v2, v4, v2
	v_cmp_ne_u32_e32 vcc, v3, v2
	v_mov_b32_e32 v1, v2
	v_mov_b64_e32 v[2:3], s[10:11]
	s_and_saveexec_b64 s[12:13], vcc
	s_cbranch_execz .LBB0_584
	global_load_dword v2, v0, s[10:11] sc1
	s_mov_b64 s[18:19], 0
	s_waitcnt vmcnt(0)
	v_cmp_lt_u32_e32 vcc, v2, v1
	s_and_saveexec_b64 s[16:17], vcc
	s_cbranch_execz .LBB0_583
	s_add_u32 s14, s6, 0x31c0200
	s_addc_u32 s15, s7, 0
	s_mov_b32 s26, 1
	s_mov_b64 s[6:7], 0
	s_branch .LBB0_576

.LBB0_578:
	global_load_dword v2, v0, s[10:11] sc1
	s_add_i32 s26, s26, 1
	s_mov_b64 s[22:23], -1
	s_waitcnt vmcnt(0)
	v_cmp_ge_u32_e32 vcc, v2, v1
	s_orn2_b64 s[20:21], vcc, exec
	s_branch .LBB0_575
